# dilated attention: wave-uniform branch to a mask-free score path when the task's key window cannot leave the line (no per-element range compares/selects)
# speedup vs baseline: 1.0081x; 1.0081x over previous
; #define DIL_LOADK(ks_, KF) do { _Pragma("unroll") for (int f = 0; f < 4; ++f) KF[f] = *(const LAS bf16x8*)(fb + (ks_) * 4096 + f * 1024); } while (0)
; __device__ __forceinline__ void phase_dilated(PP p, int chunk, int dry, unsigned char* lds_g) {
;     ...
;         const bool edge = (u0b < 64) || (u0b + 192 > L);
;         f32x4 s[5][2];
;         float mx = -1e30f;
;     ...
;         {
;             bf16x8 kfA[4], kfB[4];
;             DIL_LOADK(0, kfA);
;             DIL_LOADK(1, kfB); __builtin_amdgcn_sched_barrier(0);
;             DIL_SCORE(0, kfA); __builtin_amdgcn_sched_barrier(0);
;             DIL_LOADK(2, kfA); __builtin_amdgcn_sched_barrier(0);
;             DIL_SCORE(1, kfB); __builtin_amdgcn_sched_barrier(0);
;             DIL_LOADK(3, kfB); __builtin_amdgcn_sched_barrier(0);
;             DIL_SCORE(2, kfA); __builtin_amdgcn_sched_barrier(0);
;             DIL_LOADK(4, kfA); __builtin_amdgcn_sched_barrier(0);
;             DIL_SCORE(3, kfB); __builtin_amdgcn_sched_barrier(0);
;             DIL_SCORE(4, kfA);
.LBB0_325:
	s_nop 0
	v_lshl_add_u32 v40, s6, 16, v53
	ds_read_b128 v[42:45], v40
	ds_read_b128 v[64:67], v40 offset:1024
	ds_read_b128 v[68:71], v40 offset:2048
	ds_read_b128 v[72:75], v40 offset:3072
	ds_read_b128 v[76:79], v40 offset:4096
	ds_read_b128 v[80:83], v40 offset:5120
	ds_read_b128 v[84:87], v40 offset:6144
	ds_read_b128 v[88:91], v40 offset:7168
	s_ashr_i32 s12, s26, 11
	s_and_b32 s7, s21, 0x70
	s_bfe_u32 s8, s26, 0x40003
	s_or_b32 s7, s7, s8
	s_lshl_b32 s8, s12, 1
	s_sub_i32 s8, s20, s8
	s_lshl_b32 s27, 1, s8
	s_lshl_b32 s13, s7, 7
	s_add_i32 s7, s27, -1
	s_and_b32 s29, s7, s13
	s_add_i32 s6, s29, 0xc0
	s_cmp_gt_u32 s6, s27
	s_cselect_b64 s[6:7], -1, 0
	s_cmp_eq_u32 s29, 0
	s_cselect_b64 s[8:9], -1, 0
	s_or_b64 vcc, s[8:9], s[6:7]
	s_cbranch_vccz .Lmy_dilf_fast
	s_waitcnt lgkmcnt(0)
	v_mfma_f32_16x16x32_bf16 v[42:45], v[42:45], v[36:39], v[20:23]
	v_add_u32_e32 v57, s29, v58
	v_cmp_lt_i32_e64 s[6:7], -1, v57
	v_cmp_gt_i32_e64 s[8:9], s27, v57
	v_mfma_f32_16x16x32_bf16 v[44:47], v[64:67], v[32:35], v[42:45]
	s_and_b64 s[6:7], s[6:7], s[8:9]
	v_add_u32_e32 v55, 6, v57
	v_add_u32_e32 v63, 7, v57
	s_nop 0
	v_add_u32_e32 v42, 1, v57
	v_cmp_gt_i32_e64 s[8:9], s27, v42
	s_nop 1
	v_cndmask_b32_e64 v41, v198, v44, s[6:7]
	v_cmp_lt_i32_e64 s[6:7], -2, v57
	s_and_b64 s[6:7], s[6:7], s[8:9]
	v_cndmask_b32_e32 v41, v44, v41, vcc
	v_cndmask_b32_e64 v42, v198, v45, s[6:7]
	v_cndmask_b32_e32 v44, v45, v42, vcc
	v_add_u32_e32 v42, 2, v57
	v_cmp_lt_i32_e64 s[6:7], -3, v57
	v_cmp_gt_i32_e64 s[8:9], s27, v42
	v_mfma_f32_16x16x32_bf16 v[64:67], v[68:71], v[36:39], v[16:19]
	s_and_b64 s[6:7], s[6:7], s[8:9]
	v_cndmask_b32_e64 v42, v198, v46, s[6:7]
	v_cndmask_b32_e32 v43, v46, v42, vcc
	v_add_u32_e32 v42, 3, v57
	v_cmp_lt_i32_e64 s[6:7], -4, v57
	v_cmp_gt_i32_e64 s[8:9], s27, v42
	v_mfma_f32_16x16x32_bf16 v[64:67], v[72:75], v[32:35], v[64:67]
	s_and_b64 s[6:7], s[6:7], s[8:9]
	v_add_u32_e32 v46, 4, v57
	v_cndmask_b32_e64 v42, v198, v47, s[6:7]
	v_cmp_lt_i32_e64 s[6:7], -5, v57
	v_cmp_gt_i32_e64 s[8:9], s27, v46
	v_cndmask_b32_e32 v42, v47, v42, vcc
	s_and_b64 s[6:7], s[6:7], s[8:9]
	v_add_u32_e32 v47, 5, v57
	v_cndmask_b32_e64 v46, v198, v64, s[6:7]
	v_cmp_lt_i32_e64 s[6:7], -6, v57
	v_cmp_gt_i32_e64 s[8:9], s27, v47
	s_and_b64 s[6:7], s[6:7], s[8:9]
	v_cndmask_b32_e64 v47, v198, v65, s[6:7]
	v_cmp_lt_i32_e64 s[6:7], -7, v57
	v_cmp_gt_i32_e64 s[8:9], s27, v55
	s_and_b64 s[6:7], s[6:7], s[8:9]
	v_max3_f32 v45, v41, s73, v44
	v_cndmask_b32_e64 v55, v198, v66, s[6:7]
	v_cmp_lt_i32_e64 s[6:7], -8, v57
	v_cmp_gt_i32_e64 s[8:9], s27, v63
	v_max3_f32 v45, v45, v43, v42
	v_cndmask_b32_e32 v46, v64, v46, vcc
	v_cndmask_b32_e32 v47, v65, v47, vcc
	s_and_b64 s[6:7], s[6:7], s[8:9]
	v_max3_f32 v45, v45, v46, v47
	v_cndmask_b32_e32 v55, v66, v55, vcc
	v_cndmask_b32_e64 v57, v198, v67, s[6:7]
	v_cndmask_b32_e32 v57, v67, v57, vcc
	ds_read_b128 v[72:75], v40 offset:8192
	ds_read_b128 v[92:95], v40 offset:9216
	ds_read_b128 v[98:101], v40 offset:10240
	ds_read_b128 v[102:105], v40 offset:11264
	v_max3_f32 v63, v45, v55, v57
	v_mfma_f32_16x16x32_bf16 v[64:67], v[76:79], v[36:39], 0
	v_add_u32_e32 v96, s29, v59
	v_cmp_lt_i32_e64 s[6:7], -1, v96
	v_cmp_gt_i32_e64 s[8:9], s27, v96
	v_mfma_f32_16x16x32_bf16 v[64:67], v[80:83], v[32:35], v[64:67]
	s_and_b64 s[6:7], s[6:7], s[8:9]
	s_nop 6
	v_cndmask_b32_e64 v45, v198, v64, s[6:7]
	v_cndmask_b32_e32 v45, v64, v45, vcc
	v_add_u32_e32 v64, 1, v96
	v_cmp_lt_i32_e64 s[6:7], -2, v96
	v_cmp_gt_i32_e64 s[8:9], s27, v64
	s_and_b64 s[6:7], s[6:7], s[8:9]
	v_cndmask_b32_e64 v64, v198, v65, s[6:7]
	v_cndmask_b32_e32 v65, v65, v64, vcc
	v_max3_f32 v68, v63, v45, v65
	v_add_u32_e32 v63, 2, v96
	v_cmp_lt_i32_e64 s[6:7], -3, v96
	v_cmp_gt_i32_e64 s[8:9], s27, v63
	s_and_b64 s[6:7], s[6:7], s[8:9]
	v_cndmask_b32_e64 v63, v198, v66, s[6:7]
	v_cndmask_b32_e32 v64, v66, v63, vcc
	v_add_u32_e32 v63, 3, v96
	v_cmp_lt_i32_e64 s[6:7], -4, v96
	v_cmp_gt_i32_e64 s[8:9], s27, v63
	s_and_b64 s[6:7], s[6:7], s[8:9]
	v_cndmask_b32_e64 v63, v198, v67, s[6:7]
	v_cndmask_b32_e32 v63, v67, v63, vcc
	v_max3_f32 v76, v68, v64, v63
	v_mfma_f32_16x16x32_bf16 v[66:69], v[84:87], v[36:39], 0
	v_cmp_lt_i32_e64 s[6:7], -5, v96
	v_mfma_f32_16x16x32_bf16 v[68:71], v[88:91], v[32:35], v[66:69]
	s_nop 5
	v_add_u32_e32 v66, 4, v96
	v_cmp_gt_i32_e64 s[8:9], s27, v66
	s_and_b64 s[6:7], s[6:7], s[8:9]
	v_cndmask_b32_e64 v66, v198, v68, s[6:7]
	v_cndmask_b32_e32 v67, v68, v66, vcc
	v_add_u32_e32 v66, 5, v96
	v_cmp_lt_i32_e64 s[6:7], -6, v96
	v_cmp_gt_i32_e64 s[8:9], s27, v66
	s_and_b64 s[6:7], s[6:7], s[8:9]
	v_cndmask_b32_e64 v66, v198, v69, s[6:7]
	v_cndmask_b32_e32 v68, v69, v66, vcc
	v_add_u32_e32 v69, 6, v96
	v_cmp_lt_i32_e64 s[6:7], -7, v96
	v_cmp_gt_i32_e64 s[8:9], s27, v69
	s_and_b64 s[6:7], s[6:7], s[8:9]
	v_cndmask_b32_e64 v69, v198, v70, s[6:7]
	v_cndmask_b32_e32 v69, v70, v69, vcc
	v_add_u32_e32 v70, 7, v96
	v_cmp_lt_i32_e64 s[6:7], -8, v96
	v_cmp_gt_i32_e64 s[8:9], s27, v70
	s_and_b64 s[6:7], s[6:7], s[8:9]
	v_cndmask_b32_e64 v70, v198, v71, s[6:7]
	v_max3_f32 v66, v76, v67, v68
	v_cndmask_b32_e32 v70, v71, v70, vcc
	ds_read_b128 v[76:79], v40 offset:12288
	ds_read_b128 v[80:83], v40 offset:13312
	ds_read_b128 v[84:87], v40 offset:14336
	ds_read_b128 v[88:91], v40 offset:15360
	v_max3_f32 v71, v66, v69, v70
	s_waitcnt lgkmcnt(0)
; #define DIL_LOADK(ks_, KF) do { _Pragma("unroll") for (int f = 0; f < 4; ++f) KF[f] = *(const LAS bf16x8*)(fb + (ks_) * 4096 + f * 1024); } while (0)
; __device__ __forceinline__ void phase_dilated(PP p, int chunk, int dry, unsigned char* lds_g) {
;     ...
;         {
;             bf16x8 kfA[4], kfB[4];
;             DIL_LOADK(0, kfA);
;             DIL_LOADK(1, kfB); __builtin_amdgcn_sched_barrier(0);
;             DIL_SCORE(0, kfA); __builtin_amdgcn_sched_barrier(0);
;             DIL_LOADK(2, kfA); __builtin_amdgcn_sched_barrier(0);
;             DIL_SCORE(1, kfB); __builtin_amdgcn_sched_barrier(0);
;             DIL_LOADK(3, kfB); __builtin_amdgcn_sched_barrier(0);
;             DIL_SCORE(2, kfA); __builtin_amdgcn_sched_barrier(0);
;             DIL_LOADK(4, kfA); __builtin_amdgcn_sched_barrier(0);
;             DIL_SCORE(3, kfB); __builtin_amdgcn_sched_barrier(0);
;             DIL_SCORE(4, kfA);
	v_mfma_f32_16x16x32_bf16 v[72:75], v[72:75], v[36:39], 0
	v_add_u32_e32 v96, s29, v60
	v_cmp_lt_i32_e64 s[6:7], -1, v96
	v_cmp_gt_i32_e64 s[8:9], s27, v96
	v_mfma_f32_16x16x32_bf16 v[72:75], v[92:95], v[32:35], v[72:75]
	s_and_b64 s[6:7], s[6:7], s[8:9]
	s_nop 6
	v_cndmask_b32_e64 v66, v198, v72, s[6:7]
	v_cndmask_b32_e32 v66, v72, v66, vcc
	v_add_u32_e32 v72, 1, v96
	v_cmp_lt_i32_e64 s[6:7], -2, v96
	v_cmp_gt_i32_e64 s[8:9], s27, v72
	s_and_b64 s[6:7], s[6:7], s[8:9]
	v_cndmask_b32_e64 v72, v198, v73, s[6:7]
	v_cndmask_b32_e32 v73, v73, v72, vcc
	v_max3_f32 v92, v71, v66, v73
	v_add_u32_e32 v71, 2, v96
	v_cmp_lt_i32_e64 s[6:7], -3, v96
	v_cmp_gt_i32_e64 s[8:9], s27, v71
	s_and_b64 s[6:7], s[6:7], s[8:9]
	v_cndmask_b32_e64 v71, v198, v74, s[6:7]
	v_cndmask_b32_e32 v72, v74, v71, vcc
	v_add_u32_e32 v71, 3, v96
	v_cmp_lt_i32_e64 s[6:7], -4, v96
	v_cmp_gt_i32_e64 s[8:9], s27, v71
	s_and_b64 s[6:7], s[6:7], s[8:9]
	v_cndmask_b32_e64 v71, v198, v75, s[6:7]
	v_cndmask_b32_e32 v71, v75, v71, vcc
	v_max3_f32 v74, v92, v72, v71
	v_mfma_f32_16x16x32_bf16 v[92:95], v[98:101], v[36:39], 0
	v_add_u32_e32 v75, 4, v96
	v_cmp_lt_i32_e64 s[6:7], -5, v96
	v_cmp_gt_i32_e64 s[8:9], s27, v75
	v_mfma_f32_16x16x32_bf16 v[92:95], v[102:105], v[32:35], v[92:95]
	s_and_b64 s[6:7], s[6:7], s[8:9]
	s_nop 6
	v_cndmask_b32_e64 v75, v198, v92, s[6:7]
	v_cndmask_b32_e32 v118, v92, v75, vcc
	v_add_u32_e32 v75, 5, v96
	v_cmp_lt_i32_e64 s[6:7], -6, v96
	v_cmp_gt_i32_e64 s[8:9], s27, v75
	s_and_b64 s[6:7], s[6:7], s[8:9]
	v_cndmask_b32_e64 v75, v198, v93, s[6:7]
	v_cndmask_b32_e32 v119, v93, v75, vcc
	v_add_u32_e32 v75, 6, v96
	v_cmp_lt_i32_e64 s[6:7], -7, v96
	v_cmp_gt_i32_e64 s[8:9], s27, v75
	s_and_b64 s[6:7], s[6:7], s[8:9]
	v_cndmask_b32_e64 v75, v198, v94, s[6:7]
	v_cndmask_b32_e32 v120, v94, v75, vcc
	v_add_u32_e32 v75, 7, v96
	v_cmp_lt_i32_e64 s[6:7], -8, v96
	v_cmp_gt_i32_e64 s[8:9], s27, v75
	s_and_b64 s[6:7], s[6:7], s[8:9]
	v_max3_f32 v74, v74, v118, v119
	v_cndmask_b32_e64 v75, v198, v95, s[6:7]
	v_cndmask_b32_e32 v96, v95, v75, vcc
	ds_read_b128 v[92:95], v40 offset:16384
	ds_read_b128 v[98:101], v40 offset:17408
	ds_read_b128 v[102:105], v40 offset:18432
	ds_read_b128 v[106:109], v40 offset:19456
	v_max3_f32 v110, v74, v120, v96
	v_mfma_f32_16x16x32_bf16 v[74:77], v[76:79], v[36:39], v[12:15]
	v_add_u32_e32 v111, s29, v61
	v_cmp_lt_i32_e64 s[6:7], -1, v111
	v_cmp_gt_i32_e64 s[8:9], s27, v111
	v_mfma_f32_16x16x32_bf16 v[74:77], v[80:83], v[32:35], v[74:77]
	s_and_b64 s[6:7], s[6:7], s[8:9]
	v_add_u32_e32 v79, 4, v111
	s_nop 5
	v_cndmask_b32_e64 v78, v198, v74, s[6:7]
	v_cndmask_b32_e32 v121, v74, v78, vcc
	v_add_u32_e32 v74, 1, v111
	v_cmp_lt_i32_e64 s[6:7], -2, v111
	v_cmp_gt_i32_e64 s[8:9], s27, v74
	s_and_b64 s[6:7], s[6:7], s[8:9]
	v_cndmask_b32_e64 v74, v198, v75, s[6:7]
	v_cndmask_b32_e32 v122, v75, v74, vcc
	v_add_u32_e32 v75, 2, v111
	v_cmp_lt_i32_e64 s[6:7], -3, v111
	v_cmp_gt_i32_e64 s[8:9], s27, v75
	s_and_b64 s[6:7], s[6:7], s[8:9]
	v_cndmask_b32_e64 v75, v198, v76, s[6:7]
	v_cndmask_b32_e32 v123, v76, v75, vcc
	v_add_u32_e32 v75, 3, v111
	v_cmp_lt_i32_e64 s[6:7], -4, v111
	v_cmp_gt_i32_e64 s[8:9], s27, v75
	s_and_b64 s[6:7], s[6:7], s[8:9]
	v_cndmask_b32_e64 v75, v198, v77, s[6:7]
	v_max3_f32 v74, v110, v121, v122
	v_cndmask_b32_e32 v124, v77, v75, vcc
	v_max3_f32 v78, v74, v123, v124
	v_mfma_f32_16x16x32_bf16 v[74:77], v[84:87], v[36:39], v[8:11]
	v_cmp_lt_i32_e64 s[6:7], -5, v111
	v_cmp_gt_i32_e64 s[8:9], s27, v79
	s_and_b64 s[6:7], s[6:7], s[8:9]
	v_mfma_f32_16x16x32_bf16 v[74:77], v[88:91], v[32:35], v[74:77]
	s_nop 7
	v_cndmask_b32_e64 v79, v198, v74, s[6:7]
	v_cndmask_b32_e32 v125, v74, v79, vcc
	v_add_u32_e32 v74, 5, v111
	v_cmp_lt_i32_e64 s[6:7], -6, v111
	v_cmp_gt_i32_e64 s[8:9], s27, v74
	s_and_b64 s[6:7], s[6:7], s[8:9]
	v_cndmask_b32_e64 v74, v198, v75, s[6:7]
	v_cndmask_b32_e32 v126, v75, v74, vcc
	v_add_u32_e32 v75, 6, v111
	v_cmp_lt_i32_e64 s[6:7], -7, v111
	v_cmp_gt_i32_e64 s[8:9], s27, v75
	s_and_b64 s[6:7], s[6:7], s[8:9]
	v_cndmask_b32_e64 v75, v198, v76, s[6:7]
	v_cndmask_b32_e32 v127, v76, v75, vcc
	v_add_u32_e32 v75, 7, v111
	v_cmp_lt_i32_e64 s[6:7], -8, v111
	v_cmp_gt_i32_e64 s[8:9], s27, v75
	s_and_b64 s[6:7], s[6:7], s[8:9]
	v_cndmask_b32_e64 v75, v198, v77, s[6:7]
	v_max3_f32 v74, v78, v125, v126
	v_cndmask_b32_e32 v128, v77, v75, vcc
	v_max3_f32 v78, v74, v127, v128
	s_waitcnt lgkmcnt(0)
	v_mfma_f32_16x16x32_bf16 v[74:77], v[92:95], v[36:39], v[4:7]
	v_add_u32_e32 v79, s29, v62
	v_cmp_lt_i32_e64 s[6:7], -1, v79
	v_cmp_gt_i32_e64 s[8:9], s27, v79
	v_mfma_f32_16x16x32_bf16 v[74:77], v[98:101], v[32:35], v[74:77]
	s_and_b64 s[6:7], s[6:7], s[8:9]
	v_mfma_f32_16x16x32_bf16 v[36:39], v[102:105], v[36:39], v[0:3]
	v_mfma_f32_16x16x32_bf16 v[32:35], v[106:109], v[32:35], v[36:39]
	s_nop 4
	v_cndmask_b32_e64 v80, v198, v74, s[6:7]
	v_cndmask_b32_e32 v129, v74, v80, vcc
	v_add_u32_e32 v74, 1, v79
	v_cmp_lt_i32_e64 s[6:7], -2, v79
	v_cmp_gt_i32_e64 s[8:9], s27, v74
	s_and_b64 s[6:7], s[6:7], s[8:9]
	v_cndmask_b32_e64 v74, v198, v75, s[6:7]
	v_cndmask_b32_e32 v75, v75, v74, vcc
	v_max3_f32 v74, v78, v129, v75
	v_add_u32_e32 v78, 2, v79
	v_cmp_lt_i32_e64 s[6:7], -3, v79
	v_cmp_gt_i32_e64 s[8:9], s27, v78
	s_and_b64 s[6:7], s[6:7], s[8:9]
	v_cndmask_b32_e64 v78, v198, v76, s[6:7]
	v_cndmask_b32_e32 v130, v76, v78, vcc
	v_add_u32_e32 v76, 3, v79
	v_cmp_lt_i32_e64 s[6:7], -4, v79
	v_cmp_gt_i32_e64 s[8:9], s27, v76
	s_and_b64 s[6:7], s[6:7], s[8:9]
	v_add_u32_e32 v36, 4, v79
	v_cndmask_b32_e64 v76, v198, v77, s[6:7]
	v_cmp_lt_i32_e64 s[6:7], -5, v79
	v_cmp_gt_i32_e64 s[8:9], s27, v36
	s_and_b64 s[6:7], s[6:7], s[8:9]
	v_cndmask_b32_e64 v36, v198, v32, s[6:7]
	v_cndmask_b32_e32 v132, v32, v36, vcc
	v_add_u32_e32 v32, 5, v79
	v_cmp_lt_i32_e64 s[6:7], -6, v79
	v_cmp_gt_i32_e64 s[8:9], s27, v32
	s_and_b64 s[6:7], s[6:7], s[8:9]
	v_cndmask_b32_e64 v32, v198, v33, s[6:7]
	v_cndmask_b32_e32 v133, v33, v32, vcc
	v_add_u32_e32 v33, 6, v79
	v_cmp_lt_i32_e64 s[6:7], -7, v79
	v_cmp_gt_i32_e64 s[8:9], s27, v33
	s_and_b64 s[6:7], s[6:7], s[8:9]
	v_cndmask_b32_e64 v33, v198, v34, s[6:7]
	v_cndmask_b32_e32 v134, v34, v33, vcc
	v_add_u32_e32 v33, 7, v79
	v_cmp_lt_i32_e64 s[6:7], -8, v79
	v_cmp_gt_i32_e64 s[8:9], s27, v33
	s_and_b64 s[6:7], s[6:7], s[8:9]
	v_cndmask_b32_e32 v131, v77, v76, vcc
	v_cndmask_b32_e64 v33, v198, v35, s[6:7]
	v_max3_f32 v74, v74, v130, v131
	v_cndmask_b32_e32 v135, v35, v33, vcc
; #define DIL_LOADV(ks_, VF) do { _Pragma("unroll") for (int f = 0; f < 4; ++f) VF[f] = *(const LAS bf16x8*)(fb + 32768 + (ks_) * 4096 + f * 1024); } while (0)
; __device__ __forceinline__ void phase_dilated(PP p, int chunk, int dry, unsigned char* lds_g) {
;     ...
;         mx = fmaxf(mx, __shfl_xor(mx, 16)); mx = fmaxf(mx, __shfl_xor(mx, 32));
;         float l = 0;
;         f32x4 o[4];
; #pragma unroll
;         for (int nt = 0; nt < 4; ++nt) o[nt] = (f32x4){0.f, 0.f, 0.f, 0.f};
;     ...
;         {
;             bf16x8 vfA[4], vfB[4];
;             DIL_LOADV(0, vfA);
;             DIL_LOADV(1, vfB); __builtin_amdgcn_sched_barrier(0);
;             DIL_PV(0, vfA); __builtin_amdgcn_sched_barrier(0);
;             DIL_LOADV(2, vfA); __builtin_amdgcn_sched_barrier(0);
;             DIL_PV(1, vfB); __builtin_amdgcn_sched_barrier(0);
;             DIL_LOADV(3, vfB); __builtin_amdgcn_sched_barrier(0);
;             DIL_PV(2, vfA); __builtin_amdgcn_sched_barrier(0);
;             DIL_LOADV(4, vfA); __builtin_amdgcn_sched_barrier(0);
;             DIL_PV(3, vfB); __builtin_amdgcn_sched_barrier(0);
;             DIL_PV(4, vfA);
;         }
;     ...
;         l += __shfl_xor(l, 16); l += __shfl_xor(l, 32);
.Lmy_dilf_join:
	v_cmp_lt_i32_e32 vcc, v193, v192
	v_max3_f32 v32, v74, v132, v133
	v_max3_f32 v32, v32, v134, v135
	v_cndmask_b32_e32 v33, v190, v193, vcc
	v_lshlrev_b32_e32 v136, 2, v33
	ds_bpermute_b32 v33, v136, v32
	v_cmp_lt_i32_e32 vcc, v191, v192
	s_waitcnt lgkmcnt(0)
	v_max_f32_e32 v33, v33, v33
	v_max_f32_e32 v74, v32, v33
	v_cndmask_b32_e32 v32, v190, v191, vcc
	v_lshlrev_b32_e32 v137, 2, v32
	ds_read_b128 v[32:35], v40 offset:32768
	ds_read_b128 v[36:39], v40 offset:33792
	ds_read_b128 v[76:79], v40 offset:34816
	ds_read_b128 v[80:83], v40 offset:35840
	ds_read_b128 v[84:87], v40 offset:36864
	ds_read_b128 v[88:91], v40 offset:37888
	ds_read_b128 v[92:95], v40 offset:38912
	ds_read_b128 v[98:101], v40 offset:39936
	ds_bpermute_b32 v102, v137, v74
	s_waitcnt lgkmcnt(0)
	v_max_f32_e32 v102, v102, v102
	v_max_f32_e32 v74, v74, v102
	v_sub_f32_e32 v41, v41, v74
	v_exp_f32_e32 v41, v41
	v_sub_f32_e32 v44, v44, v74
	v_exp_f32_e32 v44, v44
	v_sub_f32_e32 v43, v43, v74
	v_exp_f32_e32 v43, v43
	v_sub_f32_e32 v42, v42, v74
	v_exp_f32_e32 v42, v42
	v_sub_f32_e32 v46, v46, v74
	v_add_f32_e32 v102, 0, v41
	v_exp_f32_e32 v46, v46
	v_sub_f32_e32 v47, v47, v74
	v_add_f32_e32 v102, v44, v102
	v_exp_f32_e32 v47, v47
	v_sub_f32_e32 v55, v55, v74
	v_add_f32_e32 v102, v43, v102
	v_exp_f32_e32 v55, v55
	v_sub_f32_e32 v57, v57, v74
	v_add_f32_e32 v106, v42, v102
	v_exp_f32_e32 v57, v57
	v_cvt_pk_bf16_f32 v102, v41, v44
	v_cvt_pk_bf16_f32 v103, v43, v42
	v_cvt_pk_bf16_f32 v104, v46, v47
	v_cvt_pk_bf16_f32 v105, v55, v57
	v_add_f32_e32 v41, v46, v106
	v_mfma_f32_16x16x32_bf16 v[32:35], v[32:35], v[102:105], 0
	v_add_f32_e32 v41, v47, v41
	v_add_f32_e32 v41, v55, v41
	v_mfma_f32_16x16x32_bf16 v[36:39], v[36:39], v[102:105], 0
	v_mfma_f32_16x16x32_bf16 v[76:79], v[76:79], v[102:105], 0
	v_mfma_f32_16x16x32_bf16 v[80:83], v[80:83], v[102:105], 0
	ds_read_b128 v[102:105], v40 offset:40960
	ds_read_b128 v[106:109], v40 offset:41984
	ds_read_b128 v[110:113], v40 offset:43008
	ds_read_b128 v[114:117], v40 offset:44032
	v_add_f32_e32 v41, v57, v41
	v_sub_f32_e32 v42, v45, v74
	v_exp_f32_e32 v42, v42
	v_sub_f32_e32 v43, v65, v74
	v_exp_f32_e32 v43, v43
	v_sub_f32_e32 v44, v64, v74
	v_exp_f32_e32 v44, v44
	v_sub_f32_e32 v45, v63, v74
	v_exp_f32_e32 v45, v45
	v_add_f32_e32 v41, v42, v41
	v_sub_f32_e32 v46, v67, v74
	v_add_f32_e32 v41, v43, v41
	v_exp_f32_e32 v46, v46
	v_sub_f32_e32 v47, v68, v74
	v_add_f32_e32 v41, v44, v41
	v_exp_f32_e32 v47, v47
	v_sub_f32_e32 v55, v69, v74
	v_sub_f32_e32 v57, v70, v74
	v_add_f32_e32 v41, v45, v41
	v_exp_f32_e32 v55, v55
	v_exp_f32_e32 v57, v57
	v_cvt_pk_bf16_f32 v42, v42, v43
	v_cvt_pk_bf16_f32 v43, v44, v45
	v_cvt_pk_bf16_f32 v44, v46, v47
	v_cvt_pk_bf16_f32 v45, v55, v57
	v_add_f32_e32 v41, v46, v41
	v_mfma_f32_16x16x32_bf16 v[32:35], v[84:87], v[42:45], v[32:35]
	v_add_f32_e32 v41, v47, v41
	v_add_f32_e32 v41, v55, v41
	v_mfma_f32_16x16x32_bf16 v[36:39], v[88:91], v[42:45], v[36:39]
	v_mfma_f32_16x16x32_bf16 v[76:79], v[92:95], v[42:45], v[76:79]
	v_mfma_f32_16x16x32_bf16 v[42:45], v[98:101], v[42:45], v[80:83]
	s_nop 2
	ds_read_b128 v[80:83], v40 offset:45056
	ds_read_b128 v[84:87], v40 offset:46080
	ds_read_b128 v[88:91], v40 offset:47104
	ds_read_b128 v[92:95], v40 offset:48128
	v_add_f32_e32 v41, v57, v41
	v_sub_f32_e32 v46, v66, v74
	v_exp_f32_e32 v46, v46
	v_sub_f32_e32 v47, v73, v74
	v_exp_f32_e32 v47, v47
	v_sub_f32_e32 v55, v72, v74
	v_exp_f32_e32 v55, v55
	v_sub_f32_e32 v57, v71, v74
	v_exp_f32_e32 v57, v57
	v_sub_f32_e32 v63, v118, v74
	v_add_f32_e32 v41, v46, v41
	v_exp_f32_e32 v63, v63
	v_sub_f32_e32 v64, v119, v74
	v_add_f32_e32 v41, v47, v41
	v_exp_f32_e32 v72, v64
	v_sub_f32_e32 v64, v120, v74
	v_add_f32_e32 v41, v55, v41
	v_exp_f32_e32 v73, v64
	v_sub_f32_e32 v64, v96, v74
	v_add_f32_e32 v41, v57, v41
	v_exp_f32_e32 v96, v64
	v_cvt_pk_bf16_f32 v64, v46, v47
	v_cvt_pk_bf16_f32 v65, v55, v57
	v_cvt_pk_bf16_f32 v66, v63, v72
	v_cvt_pk_bf16_f32 v67, v73, v96
	v_add_f32_e32 v41, v63, v41
	s_waitcnt lgkmcnt(0)
	v_mfma_f32_16x16x32_bf16 v[32:35], v[102:105], v[64:67], v[32:35]
	v_add_f32_e32 v41, v72, v41
	v_add_f32_e32 v41, v73, v41
	v_mfma_f32_16x16x32_bf16 v[36:39], v[106:109], v[64:67], v[36:39]
	v_mfma_f32_16x16x32_bf16 v[42:45], v[114:117], v[64:67], v[42:45]
	v_mfma_f32_16x16x32_bf16 v[68:71], v[110:113], v[64:67], v[76:79]
	ds_read_b128 v[64:67], v40 offset:49152
	s_nop 1
	ds_read_b128 v[76:79], v40 offset:50176
	ds_read_b128 v[98:101], v40 offset:51200
	ds_read_b128 v[102:105], v40 offset:52224
	v_add_f32_e32 v40, v96, v41
	v_sub_f32_e32 v41, v121, v74
	v_exp_f32_e32 v41, v41
	v_sub_f32_e32 v46, v122, v74
	v_exp_f32_e32 v46, v46
	v_sub_f32_e32 v47, v123, v74
	v_exp_f32_e32 v47, v47
	v_sub_f32_e32 v55, v124, v74
	v_exp_f32_e32 v55, v55
	v_sub_f32_e32 v57, v125, v74
	v_add_f32_e32 v40, v41, v40
	v_exp_f32_e32 v57, v57
	v_sub_f32_e32 v63, v126, v74
	v_add_f32_e32 v40, v46, v40
	v_exp_f32_e32 v63, v63
	v_sub_f32_e32 v72, v127, v74
	v_add_f32_e32 v40, v47, v40
	v_exp_f32_e32 v72, v72
	v_sub_f32_e32 v73, v128, v74
	v_add_f32_e32 v40, v55, v40
	v_exp_f32_e32 v73, v73
	v_cvt_pk_bf16_f32 v106, v41, v46
	v_cvt_pk_bf16_f32 v107, v47, v55
	v_cvt_pk_bf16_f32 v108, v57, v63
	v_cvt_pk_bf16_f32 v109, v72, v73
	v_add_f32_e32 v40, v57, v40
	v_mfma_f32_16x16x32_bf16 v[32:35], v[80:83], v[106:109], v[32:35]
	v_add_f32_e32 v40, v63, v40
	v_add_f32_e32 v40, v72, v40
	v_add_f32_e32 v40, v73, v40
	v_mfma_f32_16x16x32_bf16 v[36:39], v[84:87], v[106:109], v[36:39]
	v_mfma_f32_16x16x32_bf16 v[68:71], v[88:91], v[106:109], v[68:71]
	v_mfma_f32_16x16x32_bf16 v[80:83], v[92:95], v[106:109], v[42:45]
	v_sub_f32_e32 v41, v129, v74
	v_exp_f32_e32 v41, v41
	s_nop 0
	v_sub_f32_e32 v42, v75, v74
	v_exp_f32_e32 v42, v42
	v_sub_f32_e32 v43, v130, v74
	v_exp_f32_e32 v43, v43
	v_sub_f32_e32 v44, v131, v74
	v_exp_f32_e32 v44, v44
	v_add_f32_e32 v40, v41, v40
	v_add_f32_e32 v40, v42, v40
	v_add_f32_e32 v40, v43, v40
	v_add_f32_e32 v55, v44, v40
	v_sub_f32_e32 v40, v132, v74
	v_exp_f32_e32 v57, v40
	v_sub_f32_e32 v40, v133, v74
	v_exp_f32_e32 v63, v40
	v_sub_f32_e32 v40, v134, v74
	v_exp_f32_e32 v72, v40
	v_sub_f32_e32 v40, v135, v74
	v_exp_f32_e32 v73, v40
	v_add_f32_e32 v55, v57, v55
	v_add_f32_e32 v55, v63, v55
	v_add_f32_e32 v55, v72, v55
	v_add_f32_e32 v55, v73, v55
	v_cvt_pk_bf16_f32 v84, v41, v42
	v_cvt_pk_bf16_f32 v85, v43, v44
	v_cvt_pk_bf16_f32 v86, v57, v63
	ds_bpermute_b32 v57, v136, v55
	v_cvt_pk_bf16_f32 v87, v72, v73
	s_waitcnt lgkmcnt(0)
	v_add_f32_e32 v55, v55, v57
	ds_bpermute_b32 v57, v137, v55
	v_mfma_f32_16x16x32_bf16 v[40:43], v[64:67], v[84:87], v[32:35]
	s_waitcnt lgkmcnt(0)
	v_add_f32_e32 v55, v55, v57
	v_mfma_f32_16x16x32_bf16 v[44:47], v[76:79], v[84:87], v[36:39]
	v_mfma_f32_16x16x32_bf16 v[36:39], v[98:101], v[84:87], v[68:71]
	v_mfma_f32_16x16x32_bf16 v[32:35], v[102:105], v[84:87], v[80:83]
	s_and_saveexec_b64 s[6:7], s[4:5]
	s_cbranch_execz .LBB0_327
; __device__ __forceinline__ void phase_dilated(PP p, int chunk, int dry, unsigned char* lds_g) {
;     ...
;         const float rl = 1.f / l;
;         if (fq == 0 && !dry) lse[((size_t)g * 16384 + p0 + fr) * 16 + h] = mx + __log2f(l);
	s_add_i32 s27, s13, s14
	s_ashr_i32 s13, s12, 31
	s_lshl_b64 s[8:9], s[12:13], 14
	s_ashr_i32 s12, s27, 31
	s_add_u32 s8, s8, s27
	v_log_f32_e32 v57, v55
	s_addc_u32 s9, s9, s12
	v_mov_b32_e32 v65, s9
	v_or_b32_e32 v64, s8, v48
	v_lshlrev_b64 v[64:65], 6, v[64:65]
	s_lshr_b32 s8, s26, 5
	v_lshl_add_u64 v[64:65], s[0:1], 0, v[64:65]
	s_and_b32 s48, s8, 60
	v_add_f32_e32 v57, v74, v57
	v_lshl_add_u64 v[64:65], v[64:65], 0, s[48:49]
	global_store_dword v[64:65], v57, off

; #define DIL_LOADK(ks_, KF) do { _Pragma("unroll") for (int f = 0; f < 4; ++f) KF[f] = *(const LAS bf16x8*)(fb + (ks_) * 4096 + f * 1024); } while (0)
; __device__ __forceinline__ void phase_dilated(PP p, int chunk, int dry, unsigned char* lds_g) {
;     ...
;         {
;             bf16x8 kfA[4], kfB[4];
;             DIL_LOADK(0, kfA);
;             DIL_LOADK(1, kfB); __builtin_amdgcn_sched_barrier(0);
;             DIL_SCORE(0, kfA); __builtin_amdgcn_sched_barrier(0);
;             DIL_LOADK(2, kfA); __builtin_amdgcn_sched_barrier(0);
;             DIL_SCORE(1, kfB); __builtin_amdgcn_sched_barrier(0);
;             DIL_LOADK(3, kfB); __builtin_amdgcn_sched_barrier(0);
;             DIL_SCORE(2, kfA); __builtin_amdgcn_sched_barrier(0);
;             DIL_LOADK(4, kfA); __builtin_amdgcn_sched_barrier(0);
;             DIL_SCORE(3, kfB); __builtin_amdgcn_sched_barrier(0);
;             DIL_SCORE(4, kfA);
.Lmy_dilf_fast:
	s_waitcnt lgkmcnt(0)
	v_mfma_f32_16x16x32_bf16 v[42:45], v[42:45], v[36:39], v[20:23]
	v_mfma_f32_16x16x32_bf16 v[44:47], v[64:67], v[32:35], v[42:45]
	s_nop 0
	s_nop 1
	s_nop 4
	v_mov_b32_e32 v41, v44
	v_mov_b32_e32 v44, v45
	v_mfma_f32_16x16x32_bf16 v[64:67], v[68:71], v[36:39], v[16:19]
	v_mov_b32_e32 v43, v46
	v_mfma_f32_16x16x32_bf16 v[64:67], v[72:75], v[32:35], v[64:67]
	v_mov_b32_e32 v42, v47
	v_max3_f32 v45, v41, s73, v44
	v_max3_f32 v45, v45, v43, v42
	s_nop 4
	v_mov_b32_e32 v46, v64
	v_mov_b32_e32 v47, v65
	v_max3_f32 v45, v45, v46, v47
	v_mov_b32_e32 v55, v66
	v_mov_b32_e32 v57, v67
	ds_read_b128 v[72:75], v40 offset:8192
	ds_read_b128 v[92:95], v40 offset:9216
	ds_read_b128 v[98:101], v40 offset:10240
	ds_read_b128 v[102:105], v40 offset:11264
	v_max3_f32 v63, v45, v55, v57
	v_mfma_f32_16x16x32_bf16 v[64:67], v[76:79], v[36:39], 0
	v_mfma_f32_16x16x32_bf16 v[64:67], v[80:83], v[32:35], v[64:67]
	s_nop 6
	s_nop 0
	v_mov_b32_e32 v45, v64
	v_max3_f32 v68, v63, v45, v65
	v_mov_b32_e32 v64, v66
	v_mov_b32_e32 v63, v67
	v_max3_f32 v76, v68, v64, v63
	v_mfma_f32_16x16x32_bf16 v[66:69], v[84:87], v[36:39], 0
	v_mfma_f32_16x16x32_bf16 v[68:71], v[88:91], v[32:35], v[66:69]
	s_nop 5
	s_nop 1
	v_mov_b32_e32 v67, v68
	v_mov_b32_e32 v68, v69
	v_mov_b32_e32 v69, v70
	v_max3_f32 v66, v76, v67, v68
	v_mov_b32_e32 v70, v71
	ds_read_b128 v[76:79], v40 offset:12288
	ds_read_b128 v[80:83], v40 offset:13312
	ds_read_b128 v[84:87], v40 offset:14336
	ds_read_b128 v[88:91], v40 offset:15360
	v_max3_f32 v71, v66, v69, v70
	s_waitcnt lgkmcnt(0)
	v_mfma_f32_16x16x32_bf16 v[72:75], v[72:75], v[36:39], 0
	v_mfma_f32_16x16x32_bf16 v[72:75], v[92:95], v[32:35], v[72:75]
	s_nop 6
	s_nop 0
	v_mov_b32_e32 v66, v72
	v_max3_f32 v92, v71, v66, v73
	v_mov_b32_e32 v72, v74
	v_mov_b32_e32 v71, v75
	v_max3_f32 v74, v92, v72, v71
	v_mfma_f32_16x16x32_bf16 v[92:95], v[98:101], v[36:39], 0
	v_mfma_f32_16x16x32_bf16 v[92:95], v[102:105], v[32:35], v[92:95]
	s_nop 6
	s_nop 0
	v_mov_b32_e32 v118, v92
	v_mov_b32_e32 v119, v93
	v_mov_b32_e32 v120, v94
	v_max3_f32 v74, v74, v118, v119
	v_mov_b32_e32 v96, v95
	ds_read_b128 v[92:95], v40 offset:16384
	ds_read_b128 v[98:101], v40 offset:17408
	ds_read_b128 v[102:105], v40 offset:18432
	ds_read_b128 v[106:109], v40 offset:19456
	v_max3_f32 v110, v74, v120, v96
	v_mfma_f32_16x16x32_bf16 v[74:77], v[76:79], v[36:39], v[12:15]
	v_add_u32_e32 v111, s29, v61
	v_mfma_f32_16x16x32_bf16 v[74:77], v[80:83], v[32:35], v[74:77]
	s_nop 5
	s_nop 1
	v_mov_b32_e32 v121, v74
	v_mov_b32_e32 v122, v75
	v_mov_b32_e32 v123, v76
	v_max3_f32 v74, v110, v121, v122
	v_mov_b32_e32 v124, v77
	v_max3_f32 v78, v74, v123, v124
	v_mfma_f32_16x16x32_bf16 v[74:77], v[84:87], v[36:39], v[8:11]
	v_mfma_f32_16x16x32_bf16 v[74:77], v[88:91], v[32:35], v[74:77]
	s_nop 7
	v_mov_b32_e32 v125, v74
	v_mov_b32_e32 v126, v75
	v_mov_b32_e32 v127, v76
	v_max3_f32 v74, v78, v125, v126
	v_mov_b32_e32 v128, v77
	v_max3_f32 v78, v74, v127, v128
	s_waitcnt lgkmcnt(0)
	v_mfma_f32_16x16x32_bf16 v[74:77], v[92:95], v[36:39], v[4:7]
	v_add_u32_e32 v79, s29, v62
	v_mfma_f32_16x16x32_bf16 v[74:77], v[98:101], v[32:35], v[74:77]
	v_mfma_f32_16x16x32_bf16 v[36:39], v[102:105], v[36:39], v[0:3]
	v_mfma_f32_16x16x32_bf16 v[32:35], v[106:109], v[32:35], v[36:39]
	s_nop 4
	s_nop 0
	v_mov_b32_e32 v129, v74
	v_max3_f32 v74, v78, v129, v75
	v_add_u32_e32 v78, 2, v79
	v_mov_b32_e32 v130, v76
	v_add_u32_e32 v76, 3, v79
	v_add_u32_e32 v36, 4, v79
	v_mov_b32_e32 v132, v32
	v_add_u32_e32 v32, 5, v79
	v_mov_b32_e32 v133, v33
	v_mov_b32_e32 v134, v34
	v_add_u32_e32 v33, 7, v79
	v_mov_b32_e32 v131, v77
	v_max3_f32 v74, v74, v130, v131
	v_mov_b32_e32 v135, v35
	s_branch .Lmy_dilf_join
